# v33: v25 + non-temporal hint on the l1 token phase stores (fewer dirty L2 lines at its barrier)
# baseline (speedup 1.0000x reference)
.LBB0_2644:
	s_andn2_b64 vcc, exec, s[8:9]
	s_mov_b64 s[8:9], -1
	s_cbranch_vccnz .LBB0_2646
	ds_read2_b64 v[2:5], v127 offset0:13 offset1:14
	s_add_i32 s12, s16, 0xffffe800
	s_lshl_b64 s[8:9], s[12:13], 11
	v_lshl_or_b32 v6, v198, 2, s8
	v_mov_b32_e32 v7, s9
	s_waitcnt lgkmcnt(0)
	v_readfirstlane_b32 s10, v2
	v_readfirstlane_b32 s11, v3
	v_readfirstlane_b32 s8, v4
	v_readfirstlane_b32 s9, v5
	v_lshl_add_u64 v[2:3], s[10:11], 0, v[6:7]
	global_load_dword v30, v[2:3], off
	v_lshl_add_u64 v[4:5], s[8:9], 0, v[6:7]
	global_load_dword v31, v[4:5], off
	global_load_dword v32, v[2:3], off offset:256
	global_load_dword v33, v[4:5], off offset:256
	global_load_dword v34, v[2:3], off offset:512
	global_load_dword v35, v[4:5], off offset:512
	global_load_dword v36, v[2:3], off offset:768
	global_load_dword v37, v[4:5], off offset:768
	global_load_dword v38, v[2:3], off offset:1024
	global_load_dword v39, v[4:5], off offset:1024
	global_load_dword v40, v[2:3], off offset:1280
	global_load_dword v41, v[4:5], off offset:1280
	global_load_dword v42, v[2:3], off offset:1536
	global_load_dword v43, v[4:5], off offset:1536
	global_load_dword v44, v[2:3], off offset:1792
	global_load_dword v45, v[4:5], off offset:1792
	s_ashr_i32 s43, s42, 31
	s_lshl_b64 s[8:9], s[42:43], 9
	v_mov_b32_e32 v3, s9
	v_or_b32_e32 v2, s8, v198
	v_mov_b32_e32 v5, s9
	v_or_b32_e32 v4, s8, v138
	v_mov_b32_e32 v7, s9
	v_or_b32_e32 v6, s8, v140
	v_mov_b32_e32 v9, s9
	v_or_b32_e32 v8, s8, v142
	v_mov_b32_e32 v11, s9
	v_or_b32_e32 v10, s8, v144
	v_mov_b32_e32 v13, s9
	v_or_b32_e32 v12, s8, v146
	v_mov_b32_e32 v15, s9
	v_or_b32_e32 v14, s8, v148
	v_lshlrev_b64 v[2:3], 1, v[2:3]
	v_lshlrev_b64 v[4:5], 1, v[4:5]
	v_lshlrev_b64 v[6:7], 1, v[6:7]
	v_lshlrev_b64 v[8:9], 1, v[8:9]
	v_lshlrev_b64 v[10:11], 1, v[10:11]
	v_lshlrev_b64 v[12:13], 1, v[12:13]
	v_lshlrev_b64 v[14:15], 1, v[14:15]
	v_lshl_add_u64 v[16:17], s[18:19], 0, v[2:3]
	v_lshl_add_u64 v[2:3], s[20:21], 0, v[2:3]
	v_lshl_add_u64 v[18:19], s[18:19], 0, v[4:5]
	v_lshl_add_u64 v[4:5], s[20:21], 0, v[4:5]
	v_lshl_add_u64 v[20:21], s[18:19], 0, v[6:7]
	v_lshl_add_u64 v[6:7], s[20:21], 0, v[6:7]
	v_lshl_add_u64 v[22:23], s[18:19], 0, v[8:9]
	v_lshl_add_u64 v[8:9], s[20:21], 0, v[8:9]
	v_lshl_add_u64 v[24:25], s[18:19], 0, v[10:11]
	v_lshl_add_u64 v[10:11], s[20:21], 0, v[10:11]
	v_lshl_add_u64 v[26:27], s[18:19], 0, v[12:13]
	v_lshl_add_u64 v[12:13], s[20:21], 0, v[12:13]
	v_lshl_add_u64 v[28:29], s[18:19], 0, v[14:15]
	s_waitcnt vmcnt(14)
	v_cvt_pk_bf16_f32 v31, v31, s0
	s_waitcnt vmcnt(13)
	v_cvt_pk_bf16_f32 v32, v32, s0
	s_waitcnt vmcnt(12)
	v_cvt_pk_bf16_f32 v33, v33, s0
	s_waitcnt vmcnt(11)
	v_cvt_pk_bf16_f32 v34, v34, s0
	s_waitcnt vmcnt(10)
	v_cvt_pk_bf16_f32 v35, v35, s0
	s_waitcnt vmcnt(9)
	v_cvt_pk_bf16_f32 v36, v36, s0
	s_waitcnt vmcnt(8)
	v_cvt_pk_bf16_f32 v37, v37, s0
	s_waitcnt vmcnt(7)
	v_cvt_pk_bf16_f32 v38, v38, s0
	s_waitcnt vmcnt(6)
	v_cvt_pk_bf16_f32 v39, v39, s0
	s_waitcnt vmcnt(5)
	v_cvt_pk_bf16_f32 v40, v40, s0
	s_waitcnt vmcnt(4)
	v_cvt_pk_bf16_f32 v41, v41, s0
	s_waitcnt vmcnt(3)
	v_cvt_pk_bf16_f32 v42, v42, s0
	v_cvt_pk_bf16_f32 v30, v30, s0
	global_store_short v[16:17], v30, off nt
	global_store_short v[2:3], v31, off nt
	global_store_short v[18:19], v32, off nt
	global_store_short v[4:5], v33, off nt
	global_store_short v[20:21], v34, off nt
	global_store_short v[6:7], v35, off nt
	global_store_short v[22:23], v36, off nt
	global_store_short v[8:9], v37, off nt
	global_store_short v[24:25], v38, off nt
	global_store_short v[10:11], v39, off nt
	global_store_short v[26:27], v40, off nt
	global_store_short v[12:13], v41, off nt
	global_store_short v[28:29], v42, off nt
	s_waitcnt vmcnt(15)
	v_cvt_pk_bf16_f32 v4, v43, s0
	v_lshl_add_u64 v[2:3], s[20:21], 0, v[14:15]
	global_store_short v[2:3], v4, off nt
	v_mov_b32_e32 v3, s9
	v_or_b32_e32 v2, s8, v150
	v_lshlrev_b64 v[2:3], 1, v[2:3]
	s_waitcnt vmcnt(15)
	v_cvt_pk_bf16_f32 v6, v44, s0
	v_lshl_add_u64 v[4:5], s[18:19], 0, v[2:3]
	global_store_short v[4:5], v6, off nt
	s_waitcnt vmcnt(15)
	v_cvt_pk_bf16_f32 v4, v45, s0
	v_lshl_add_u64 v[2:3], s[20:21], 0, v[2:3]
	s_mov_b64 s[8:9], 0
	global_store_short v[2:3], v4, off nt

.LBB0_2684:
	s_waitcnt vmcnt(33)
	v_pk_mul_f32 v[196:197], v[188:189], v[188:189]
	s_nop 0
	v_add_f32_e32 v196, v196, v197
	s_nop 1
	v_add_f32_dpp v196, v196, v196 quad_perm:[1,0,3,2] row_mask:0xf bank_mask:0xf bound_ctrl:1
	s_nop 1
	v_add_f32_dpp v196, v196, v196 quad_perm:[2,3,0,1] row_mask:0xf bank_mask:0xf bound_ctrl:1
	s_nop 1
	v_add_f32_dpp v196, v196, v196 row_half_mirror row_mask:0xf bank_mask:0xf bound_ctrl:1
	s_nop 1
	v_add_f32_dpp v196, v196, v196 row_mirror row_mask:0xf bank_mask:0xf bound_ctrl:1
	s_nop 0
	v_readlane_b32 s9, v196, 0
	v_readlane_b32 s12, v196, 16
	v_readlane_b32 s11, v196, 32
	v_readlane_b32 s43, v196, 48
	s_waitcnt vmcnt(29)
	v_pk_mul_f32 v[196:197], v[186:187], v[186:187]
	s_nop 0
	v_add_f32_e32 v196, v196, v197
	v_mov_b32_e32 v197, s12
	v_mov_b32_e32 v203, s43
	v_add_f32_dpp v196, v196, v196 quad_perm:[1,0,3,2] row_mask:0xf bank_mask:0xf bound_ctrl:1
	s_nop 1
	v_add_f32_dpp v196, v196, v196 quad_perm:[2,3,0,1] row_mask:0xf bank_mask:0xf bound_ctrl:1
	s_nop 1
	v_add_f32_dpp v196, v196, v196 row_half_mirror row_mask:0xf bank_mask:0xf bound_ctrl:1
	s_nop 1
	v_add_f32_dpp v196, v196, v196 row_mirror row_mask:0xf bank_mask:0xf bound_ctrl:1
	s_nop 0
	v_readlane_b32 s46, v196, 16
	v_readlane_b32 s47, v196, 48
	v_readlane_b32 s8, v196, 0
	v_readlane_b32 s10, v196, 32
	v_mov_b32_e32 v196, s46
	v_mov_b32_e32 v202, s47
	v_pk_add_f32 v[196:197], s[8:9], v[196:197]
	v_pk_add_f32 v[202:203], s[10:11], v[202:203]
	s_nop 0
	v_cndmask_b32_e64 v197, v203, v197, s[2:3]
	v_cndmask_b32_e64 v196, v202, v196, s[2:3]
	s_waitcnt vmcnt(23)
	v_pk_fma_f32 v[202:203], v[196:197], s[38:39], v[172:173] op_sel_hi:[1,0,0]
	s_nop 0
	v_mul_f32_e32 v196, 0x4b800000, v203
	v_cmp_gt_f32_e32 vcc, s23, v203
	s_nop 1
	v_cndmask_b32_e32 v196, v203, v196, vcc
	v_rsq_f32_e32 v203, v196
	v_lshl_add_u64 v[196:197], s[14:15], 0, v[158:159]
	v_mul_f32_e32 v204, 0x45800000, v203
	v_cndmask_b32_e32 v203, v203, v204, vcc
	v_mul_f32_e32 v189, v189, v203
	v_mul_f32_e32 v188, v188, v203
	s_waitcnt vmcnt(1)
	v_mul_f32_e32 v204, v195, v189
	v_mul_f32_e32 v188, v194, v188
	v_pk_mul_f32 v[204:205], v[190:191], v[204:205] op_sel:[1,0] op_sel_hi:[0,0]
	v_pk_fma_f32 v[206:207], v[190:191], v[188:189], v[204:205] neg_lo:[0,0,1] neg_hi:[0,0,1]
	v_pk_fma_f32 v[188:189], v[190:191], v[188:189], v[204:205] op_sel_hi:[1,0,1]
	v_cmp_gt_f32_e32 vcc, s23, v202
	v_mul_f32_e32 v188, 0x4b800000, v202
	v_mov_b32_e32 v207, v189
	v_cndmask_b32_e32 v188, v202, v188, vcc
	v_rsq_f32_e32 v202, v188
	v_pk_mul_f32 v[188:189], v[206:207], s[40:41] op_sel_hi:[1,0]
	s_nop 0
	v_cvt_pk_bf16_f32 v188, v188, v189
	global_store_dword v[196:197], v188, off offset:-512 nt
	v_mul_f32_e32 v188, 0x45800000, v202
	v_cndmask_b32_e32 v188, v202, v188, vcc
	v_pk_mul_f32 v[186:187], v[186:187], v[188:189] op_sel_hi:[1,0]
	v_cndmask_b32_e64 v188, 0, 1, s[44:45]
	v_cmp_ne_u32_e64 s[8:9], 1, v188
	s_andn2_b64 vcc, exec, s[44:45]
	s_waitcnt vmcnt(1)
	v_pk_mul_f32 v[188:189], v[192:193], v[186:187]
	s_cbranch_vccnz .LBB0_2686
	ds_read_b64 v[186:187], v127 offset:408
	s_waitcnt lgkmcnt(0)
	v_readfirstlane_b32 s10, v186
	v_readfirstlane_b32 s11, v187
	s_nop 1
	v_lshl_add_u64 v[186:187], s[10:11], 0, v[160:161]
	v_lshl_add_u64 v[186:187], v[186:187], 0, s[26:27]
	v_add_co_u32_e32 v186, vcc, 0x1e80000, v186
	s_nop 1
	v_addc_co_u32_e32 v187, vcc, 0, v187, vcc
	global_store_dwordx2 v[186:187], v[188:189], off nt
.LBB0_2686:
	v_pk_mov_b32 v[186:187], v[190:191], v[190:191] op_sel:[1,0]
	s_ashr_i32 s43, s42, 31
	v_pk_mul_f32 v[202:203], v[186:187], v[188:189] op_sel:[0,1]
	s_lshl_b64 s[10:11], s[42:43], 10
	v_pk_fma_f32 v[204:205], v[190:191], v[188:189], v[202:203] neg_lo:[0,0,1] neg_hi:[0,0,1]
	v_pk_fma_f32 v[188:189], v[190:191], v[188:189], v[202:203] op_sel_hi:[1,0,1]
	v_pk_mul_f32 v[202:203], v[184:185], v[184:185]
	v_cvt_pk_bf16_f32 v204, v204, v189
	v_add_f32_e32 v188, v202, v203
	v_pk_mul_f32 v[202:203], v[182:183], v[182:183]
	s_nop 0
	v_add_f32_dpp v188, v188, v188 quad_perm:[1,0,3,2] row_mask:0xf bank_mask:0xf bound_ctrl:1
	s_nop 1
	v_add_f32_dpp v188, v188, v188 quad_perm:[2,3,0,1] row_mask:0xf bank_mask:0xf bound_ctrl:1
	s_nop 1
	v_add_f32_dpp v188, v188, v188 row_half_mirror row_mask:0xf bank_mask:0xf bound_ctrl:1
	s_nop 1
	v_add_f32_dpp v188, v188, v188 row_mirror row_mask:0xf bank_mask:0xf bound_ctrl:1
	s_nop 0
	v_readlane_b32 s43, v188, 0
	v_readlane_b32 s12, v188, 16
	v_readlane_b32 s45, v188, 32
	v_readlane_b32 s46, v188, 48
	v_add_f32_e32 v188, v202, v203
	v_mov_b32_e32 v203, s12
	v_mov_b32_e32 v207, s46
	v_add_f32_dpp v188, v188, v188 quad_perm:[1,0,3,2] row_mask:0xf bank_mask:0xf bound_ctrl:1
	s_nop 1
	v_add_f32_dpp v188, v188, v188 quad_perm:[2,3,0,1] row_mask:0xf bank_mask:0xf bound_ctrl:1
	s_nop 1
	v_add_f32_dpp v188, v188, v188 row_half_mirror row_mask:0xf bank_mask:0xf bound_ctrl:1
	s_nop 1
	v_add_f32_dpp v188, v188, v188 row_mirror row_mask:0xf bank_mask:0xf bound_ctrl:1
	s_nop 0
	v_readlane_b32 s47, v188, 16
	v_readlane_b32 s49, v188, 48
	v_readlane_b32 s42, v188, 0
	v_readlane_b32 s44, v188, 32
	v_mov_b32_e32 v202, s47
	v_mov_b32_e32 v206, s49
	v_pk_add_f32 v[202:203], s[42:43], v[202:203]
	v_pk_add_f32 v[206:207], s[44:45], v[206:207]
	s_nop 0
	v_cndmask_b32_e64 v203, v207, v203, s[2:3]
	v_cndmask_b32_e64 v202, v206, v202, s[2:3]
	v_pk_fma_f32 v[202:203], v[202:203], s[38:39], v[172:173] op_sel_hi:[1,0,0]
	s_nop 0
	v_mul_f32_e32 v188, 0x4b800000, v203
	v_cmp_gt_f32_e32 vcc, s23, v203
	s_nop 1
	v_cndmask_b32_e32 v188, v203, v188, vcc
	v_rsq_f32_e32 v203, v188
	v_lshl_add_u64 v[188:189], v[152:153], 0, s[10:11]
	global_store_dword v[188:189], v204, off nt
	v_mul_f32_e32 v204, 0x45800000, v203
	v_cndmask_b32_e32 v203, v203, v204, vcc
	v_mul_f32_e32 v185, v185, v203
	v_mul_f32_e32 v184, v184, v203
	v_mul_f32_e32 v204, v195, v185
	v_mul_f32_e32 v184, v194, v184
	v_pk_mul_f32 v[204:205], v[186:187], v[204:205] op_sel_hi:[1,0]
	v_cmp_gt_f32_e32 vcc, s23, v202
	v_pk_fma_f32 v[206:207], v[190:191], v[184:185], v[204:205] neg_lo:[0,0,1] neg_hi:[0,0,1]
	v_pk_fma_f32 v[184:185], v[190:191], v[184:185], v[204:205] op_sel_hi:[1,0,1]
	s_nop 0
	v_mul_f32_e32 v184, 0x4b800000, v202
	v_cndmask_b32_e32 v184, v202, v184, vcc
	v_rsq_f32_e32 v202, v184
	v_mov_b32_e32 v207, v185
	v_pk_mul_f32 v[184:185], v[206:207], s[40:41] op_sel_hi:[1,0]
	s_nop 0
	v_cvt_pk_bf16_f32 v184, v184, v185
	global_store_dword v[196:197], v184, off offset:-256 nt
	v_mul_f32_e32 v184, 0x45800000, v202
	v_cndmask_b32_e32 v184, v202, v184, vcc
	v_pk_mul_f32 v[182:183], v[182:183], v[184:185] op_sel_hi:[1,0]
	s_and_b64 vcc, exec, s[8:9]
	v_pk_mul_f32 v[182:183], v[192:193], v[182:183]
	s_cbranch_vccnz .LBB0_2688
	ds_read_b64 v[184:185], v127 offset:408
	s_waitcnt lgkmcnt(0)
	v_readfirstlane_b32 s42, v184
	v_readfirstlane_b32 s43, v185
	s_nop 1
	v_lshl_add_u64 v[184:185], s[42:43], 0, v[160:161]
	v_lshl_add_u64 v[184:185], v[184:185], 0, s[26:27]
	v_add_co_u32_e32 v184, vcc, 0x1e80000, v184
	s_nop 1
	v_addc_co_u32_e32 v185, vcc, 0, v185, vcc
	global_store_dwordx2 v[184:185], v[182:183], off offset:512 nt
.LBB0_2688:
	v_pk_mul_f32 v[184:185], v[186:187], v[182:183] op_sel:[0,1]
	v_pk_mul_f32 v[204:205], v[180:181], v[180:181]
	v_pk_fma_f32 v[202:203], v[190:191], v[182:183], v[184:185] neg_lo:[0,0,1] neg_hi:[0,0,1]
	v_pk_fma_f32 v[182:183], v[190:191], v[182:183], v[184:185] op_sel_hi:[1,0,1]
	v_add_f32_e32 v203, v204, v205
	v_pk_mul_f32 v[204:205], v[178:179], v[178:179]
	v_cvt_pk_bf16_f32 v182, v202, v183
	v_add_f32_dpp v203, v203, v203 quad_perm:[1,0,3,2] row_mask:0xf bank_mask:0xf bound_ctrl:1
	global_store_dword v[188:189], v182, off offset:256 nt
	s_nop 0
	v_add_f32_dpp v203, v203, v203 quad_perm:[2,3,0,1] row_mask:0xf bank_mask:0xf bound_ctrl:1
	s_nop 1
	v_add_f32_dpp v203, v203, v203 row_half_mirror row_mask:0xf bank_mask:0xf bound_ctrl:1
	s_nop 1
	v_add_f32_dpp v203, v203, v203 row_mirror row_mask:0xf bank_mask:0xf bound_ctrl:1
	s_nop 0
	v_readlane_b32 s43, v203, 0
	v_readlane_b32 s12, v203, 16
	v_readlane_b32 s45, v203, 32
	v_readlane_b32 s46, v203, 48
	v_add_f32_e32 v203, v204, v205
	v_mov_b32_e32 v205, s12
	v_mov_b32_e32 v207, s46
	v_add_f32_dpp v203, v203, v203 quad_perm:[1,0,3,2] row_mask:0xf bank_mask:0xf bound_ctrl:1
	s_nop 1
	v_add_f32_dpp v203, v203, v203 quad_perm:[2,3,0,1] row_mask:0xf bank_mask:0xf bound_ctrl:1
	s_nop 1
	v_add_f32_dpp v203, v203, v203 row_half_mirror row_mask:0xf bank_mask:0xf bound_ctrl:1
	s_nop 1
	v_add_f32_dpp v203, v203, v203 row_mirror row_mask:0xf bank_mask:0xf bound_ctrl:1
	s_nop 0
	v_readlane_b32 s47, v203, 16
	v_readlane_b32 s49, v203, 48
	v_readlane_b32 s42, v203, 0
	v_readlane_b32 s44, v203, 32
	v_mov_b32_e32 v204, s47
	v_mov_b32_e32 v206, s49
	v_pk_add_f32 v[204:205], s[42:43], v[204:205]
	v_pk_add_f32 v[206:207], s[44:45], v[206:207]
	s_nop 0
	v_cndmask_b32_e64 v205, v207, v205, s[2:3]
	v_cndmask_b32_e64 v204, v206, v204, s[2:3]
	v_pk_fma_f32 v[204:205], v[204:205], s[38:39], v[172:173] op_sel_hi:[1,0,0]
	s_nop 0
	v_mul_f32_e32 v203, 0x4b800000, v205
	v_cmp_gt_f32_e32 vcc, s23, v205
	s_nop 1
	v_cndmask_b32_e32 v203, v205, v203, vcc
	v_rsq_f32_e32 v203, v203
	s_nop 0
	v_mul_f32_e32 v182, 0x45800000, v203
	v_cndmask_b32_e32 v182, v203, v182, vcc
	v_mul_f32_e32 v181, v181, v182
	v_mul_f32_e32 v180, v180, v182
	v_mul_f32_e32 v182, v195, v181
	v_mul_f32_e32 v180, v194, v180
	v_pk_mul_f32 v[182:183], v[186:187], v[182:183] op_sel_hi:[1,0]
	v_cmp_gt_f32_e32 vcc, s23, v204
	v_pk_fma_f32 v[184:185], v[190:191], v[180:181], v[182:183] neg_lo:[0,0,1] neg_hi:[0,0,1]
	v_pk_fma_f32 v[180:181], v[190:191], v[180:181], v[182:183] op_sel_hi:[1,0,1]
	s_nop 0
	v_mul_f32_e32 v180, 0x4b800000, v204
	v_cndmask_b32_e32 v180, v204, v180, vcc
	v_rsq_f32_e32 v182, v180
	v_mov_b32_e32 v185, v181
	v_pk_mul_f32 v[180:181], v[184:185], s[40:41] op_sel_hi:[1,0]
	s_nop 0
	v_cvt_pk_bf16_f32 v180, v180, v181
	global_store_dword v[196:197], v180, off nt
	v_mul_f32_e32 v180, 0x45800000, v182
	v_cndmask_b32_e32 v180, v182, v180, vcc
	v_pk_mul_f32 v[178:179], v[178:179], v[180:181] op_sel_hi:[1,0]
	s_and_b64 vcc, exec, s[8:9]
	v_pk_mul_f32 v[178:179], v[192:193], v[178:179]
	s_cbranch_vccnz .LBB0_2690
	ds_read_b64 v[180:181], v127 offset:408
	s_waitcnt lgkmcnt(0)
	v_readfirstlane_b32 s42, v180
	v_readfirstlane_b32 s43, v181
	s_nop 1
	v_lshl_add_u64 v[180:181], s[42:43], 0, v[160:161]
	v_lshl_add_u64 v[180:181], v[180:181], 0, s[26:27]
	v_add_co_u32_e32 v180, vcc, 0x1e80000, v180
	s_nop 1
	v_addc_co_u32_e32 v181, vcc, 0, v181, vcc
	global_store_dwordx2 v[180:181], v[178:179], off offset:1024 nt
.LBB0_2690:
	v_pk_mul_f32 v[180:181], v[186:187], v[178:179] op_sel:[0,1]
	v_pk_mul_f32 v[184:185], v[176:177], v[176:177]
	v_pk_fma_f32 v[182:183], v[190:191], v[178:179], v[180:181] neg_lo:[0,0,1] neg_hi:[0,0,1]
	v_pk_fma_f32 v[178:179], v[190:191], v[178:179], v[180:181] op_sel_hi:[1,0,1]
	v_add_f32_e32 v183, v184, v185
	v_pk_mul_f32 v[184:185], v[174:175], v[174:175]
	v_cvt_pk_bf16_f32 v178, v182, v179
	v_add_f32_dpp v183, v183, v183 quad_perm:[1,0,3,2] row_mask:0xf bank_mask:0xf bound_ctrl:1
	global_store_dword v[188:189], v178, off offset:512 nt
	s_nop 0
	v_add_f32_dpp v183, v183, v183 quad_perm:[2,3,0,1] row_mask:0xf bank_mask:0xf bound_ctrl:1
	s_nop 1
	v_add_f32_dpp v183, v183, v183 row_half_mirror row_mask:0xf bank_mask:0xf bound_ctrl:1
	s_nop 1
	v_add_f32_dpp v183, v183, v183 row_mirror row_mask:0xf bank_mask:0xf bound_ctrl:1
	s_nop 0
	v_readlane_b32 s43, v183, 0
	v_readlane_b32 s12, v183, 16
	v_readlane_b32 s45, v183, 32
	v_readlane_b32 s46, v183, 48
	v_add_f32_e32 v183, v184, v185
	v_mov_b32_e32 v185, s12
	v_mov_b32_e32 v203, s46
	v_add_f32_dpp v183, v183, v183 quad_perm:[1,0,3,2] row_mask:0xf bank_mask:0xf bound_ctrl:1
	s_nop 1
	v_add_f32_dpp v183, v183, v183 quad_perm:[2,3,0,1] row_mask:0xf bank_mask:0xf bound_ctrl:1
	s_nop 1
	v_add_f32_dpp v183, v183, v183 row_half_mirror row_mask:0xf bank_mask:0xf bound_ctrl:1
	s_nop 1
	v_add_f32_dpp v183, v183, v183 row_mirror row_mask:0xf bank_mask:0xf bound_ctrl:1
	s_nop 0
	v_readlane_b32 s47, v183, 16
	v_readlane_b32 s49, v183, 48
	v_readlane_b32 s42, v183, 0
	v_readlane_b32 s44, v183, 32
	v_mov_b32_e32 v184, s47
	v_mov_b32_e32 v202, s49
	v_pk_add_f32 v[184:185], s[42:43], v[184:185]
	v_pk_add_f32 v[202:203], s[44:45], v[202:203]
	s_nop 0
	v_cndmask_b32_e64 v185, v203, v185, s[2:3]
	v_cndmask_b32_e64 v184, v202, v184, s[2:3]
	v_pk_fma_f32 v[184:185], v[184:185], s[38:39], v[172:173] op_sel_hi:[1,0,0]
	s_nop 0
	v_mul_f32_e32 v183, 0x4b800000, v185
	v_cmp_gt_f32_e32 vcc, s23, v185
	s_nop 1
	v_cndmask_b32_e32 v183, v185, v183, vcc
	v_rsq_f32_e32 v183, v183
	s_nop 0
	v_mul_f32_e32 v178, 0x45800000, v183
	v_cndmask_b32_e32 v178, v183, v178, vcc
	v_mul_f32_e32 v177, v177, v178
	v_mul_f32_e32 v176, v176, v178
	v_mul_f32_e32 v178, v195, v177
	v_mul_f32_e32 v176, v194, v176
	v_pk_mul_f32 v[178:179], v[186:187], v[178:179] op_sel_hi:[1,0]
	v_cmp_gt_f32_e32 vcc, s23, v184
	v_pk_fma_f32 v[180:181], v[190:191], v[176:177], v[178:179] neg_lo:[0,0,1] neg_hi:[0,0,1]
	v_pk_fma_f32 v[176:177], v[190:191], v[176:177], v[178:179] op_sel_hi:[1,0,1]
	s_nop 0
	v_mul_f32_e32 v176, 0x4b800000, v184
	v_cndmask_b32_e32 v176, v184, v176, vcc
	v_rsq_f32_e32 v178, v176
	v_mov_b32_e32 v181, v177
	v_pk_mul_f32 v[176:177], v[180:181], s[40:41] op_sel_hi:[1,0]
	s_nop 0
	v_cvt_pk_bf16_f32 v176, v176, v177
	global_store_dword v[196:197], v176, off offset:256 nt
	v_mul_f32_e32 v176, 0x45800000, v178
	v_cndmask_b32_e32 v176, v178, v176, vcc
	v_pk_mul_f32 v[174:175], v[174:175], v[176:177] op_sel_hi:[1,0]
	s_and_b64 vcc, exec, s[8:9]
	v_pk_mul_f32 v[174:175], v[192:193], v[174:175]
	s_cbranch_vccnz .LBB0_2692
	ds_read_b64 v[176:177], v127 offset:408
	s_waitcnt lgkmcnt(0)
	v_readfirstlane_b32 s42, v176
	v_readfirstlane_b32 s43, v177
	s_nop 1
	v_lshl_add_u64 v[176:177], s[42:43], 0, v[160:161]
	v_lshl_add_u64 v[176:177], v[176:177], 0, s[26:27]
	v_add_co_u32_e32 v176, vcc, 0x1e80000, v176
	s_nop 1
	v_addc_co_u32_e32 v177, vcc, 0, v177, vcc
	global_store_dwordx2 v[176:177], v[174:175], off offset:1536 nt
.LBB0_2692:
	v_pk_mul_f32 v[176:177], v[186:187], v[174:175] op_sel:[0,1]
	s_and_b64 vcc, exec, s[8:9]
	v_pk_fma_f32 v[178:179], v[190:191], v[174:175], v[176:177] neg_lo:[0,0,1] neg_hi:[0,0,1]
	v_pk_fma_f32 v[174:175], v[190:191], v[174:175], v[176:177] op_sel_hi:[1,0,1]
	s_nop 0
	v_cvt_pk_bf16_f32 v174, v178, v175
	global_store_dword v[188:189], v174, off offset:768 nt
	s_cbranch_vccnz .LBB0_2694
	ds_read_b64 v[174:175], v127 offset:408
	s_waitcnt lgkmcnt(0)
	v_readfirstlane_b32 s42, v174
	v_readfirstlane_b32 s43, v175
	s_nop 1
	v_lshl_add_u64 v[174:175], s[42:43], 0, v[126:127]
	v_lshl_add_u64 v[174:175], v[174:175], 0, s[26:27]
	v_add_co_u32_e32 v174, vcc, 0x2680000, v174
	s_nop 1
	v_addc_co_u32_e32 v175, vcc, 0, v175, vcc
	global_store_dword v[174:175], v200, off nt
	global_store_dword v[174:175], v201, off offset:256 nt
	global_store_dword v[174:175], v173, off offset:512 nt
	global_store_dword v[174:175], v151, off offset:768 nt
.LBB0_2694:
	v_cvt_pk_bf16_f32 v177, v200, s0
	v_lshl_add_u64 v[174:175], v[154:155], 0, s[10:11]
	v_cvt_pk_bf16_f32 v173, v173, s0
	v_cvt_pk_bf16_f32 v151, v151, s0
	s_and_b64 vcc, exec, s[8:9]
	v_cvt_pk_bf16_f32 v176, v201, s0
	global_store_short v[174:175], v177, off nt
	global_store_short v[174:175], v176, off offset:128 nt
	global_store_short v[174:175], v173, off offset:256 nt
	global_store_short v[174:175], v151, off offset:384 nt
	s_cbranch_vccnz .LBB0_2696
	ds_read_b64 v[176:177], v127 offset:408
	s_waitcnt lgkmcnt(0)
	v_readfirstlane_b32 s8, v176
	v_readfirstlane_b32 s9, v177
	s_nop 1
	v_lshl_add_u64 v[176:177], s[8:9], 0, v[126:127]
	v_lshl_add_u64 v[176:177], v[176:177], 0, s[26:27]
	v_add_co_u32_e32 v176, vcc, 0x2680000, v176
	s_nop 1
	v_addc_co_u32_e32 v177, vcc, 0, v177, vcc
	global_store_dword v[176:177], v147, off offset:1024 nt
	global_store_dword v[176:177], v149, off offset:1280 nt
	global_store_dword v[176:177], v145, off offset:1536 nt
	global_store_dword v[176:177], v143, off offset:1792 nt
.LBB0_2696:
	v_pk_add_f32 v[6:7], v[10:11], v[6:7]
	v_pk_add_f32 v[8:9], v[12:13], v[8:9]
	v_pk_fma_f32 v[6:7], v[6:7], 0.5, v[2:3] op_sel_hi:[1,0,1] neg_lo:[0,0,1] neg_hi:[0,0,1]
	v_xor_b32_e32 v11, 0x80000000, v5
	v_pk_fma_f32 v[2:3], v[14:15], v[6:7], v[2:3]
	v_cvt_pk_bf16_f32 v6, v149, s0
	v_cvt_pk_bf16_f32 v7, v147, s0
	global_store_short v[174:175], v7, off offset:512 nt
	global_store_short v[174:175], v6, off offset:640 nt
	v_cvt_pk_bf16_f32 v6, v145, s0
	v_xor_b32_e32 v10, 0x80000000, v4
	global_store_short v[174:175], v6, off offset:768 nt
	v_cvt_pk_bf16_f32 v6, v143, s0
	v_pk_fma_f32 v[8:9], v[8:9], 0.5, v[10:11] op_sel_hi:[1,0,1]
	global_store_short v[174:175], v6, off offset:896 nt
	v_lshl_add_u64 v[6:7], s[14:15], 0, v[166:167]
	v_pk_add_f32 v[22:23], v[26:27], v[22:23]
	v_pk_add_f32 v[24:25], v[28:29], v[24:25]
	v_xor_b32_e32 v27, 0x80000000, v21
	v_xor_b32_e32 v26, 0x80000000, v20
	v_pk_fma_f32 v[4:5], v[16:17], v[8:9], v[4:5]
	v_add_co_u32_e32 v8, vcc, s39, v6
	v_pk_add_f32 v[38:39], v[42:43], v[38:39]
	v_pk_add_f32 v[40:41], v[44:45], v[40:41]
	v_xor_b32_e32 v43, 0x80000000, v37
	v_xor_b32_e32 v42, 0x80000000, v36
	v_pk_fma_f32 v[24:25], v[24:25], 0.5, v[26:27] op_sel_hi:[1,0,1]
	v_pk_fma_f32 v[22:23], v[22:23], 0.5, v[18:19] op_sel_hi:[1,0,1] neg_lo:[0,0,1] neg_hi:[0,0,1]
	v_addc_co_u32_e32 v9, vcc, 0, v7, vcc
	v_pk_add_f32 v[54:55], v[58:59], v[54:55]
	v_pk_add_f32 v[56:57], v[60:61], v[56:57]
	v_xor_b32_e32 v59, 0x80000000, v53
	v_xor_b32_e32 v58, 0x80000000, v52
	v_pk_fma_f32 v[40:41], v[40:41], 0.5, v[42:43] op_sel_hi:[1,0,1]
	v_pk_fma_f32 v[38:39], v[38:39], 0.5, v[34:35] op_sel_hi:[1,0,1] neg_lo:[0,0,1] neg_hi:[0,0,1]
	v_pk_fma_f32 v[20:21], v[32:33], v[24:25], v[20:21]
	v_pk_fma_f32 v[18:19], v[30:31], v[22:23], v[18:19]
	global_store_dwordx4 v[8:9], v[2:5], off nt
	global_store_dwordx4 v[8:9], v[18:21], off offset:16 nt
	v_pk_fma_f32 v[56:57], v[56:57], 0.5, v[58:59] op_sel_hi:[1,0,1]
	v_add_co_u32_e32 v2, vcc, s41, v6
	v_pk_fma_f32 v[54:55], v[54:55], 0.5, v[50:51] op_sel_hi:[1,0,1] neg_lo:[0,0,1] neg_hi:[0,0,1]
	v_pk_fma_f32 v[36:37], v[48:49], v[40:41], v[36:37]
	v_pk_fma_f32 v[34:35], v[46:47], v[38:39], v[34:35]
	v_addc_co_u32_e32 v3, vcc, 0, v7, vcc
	v_pk_fma_f32 v[52:53], v[64:65], v[56:57], v[52:53]
	v_pk_fma_f32 v[50:51], v[62:63], v[54:55], v[50:51]
	global_store_dwordx4 v[2:3], v[34:37], off nt
	global_store_dwordx4 v[2:3], v[50:53], off offset:16 nt
	v_pk_mul_f32 v[2:3], v[36:37], v[108:109]
	v_pk_mul_f32 v[8:9], v[34:35], v[106:107]
	v_pk_mul_f32 v[4:5], v[2:3], v[2:3]
	v_pk_mul_f32 v[14:15], v[8:9], v[8:9]
	v_pk_mul_f32 v[10:11], v[52:53], v[100:101]
	v_pk_mul_f32 v[12:13], v[50:51], v[98:99]
	v_pk_mov_b32 v[16:17], v[14:15], v[4:5] op_sel:[1,0]
	v_mov_b32_e32 v15, v5
	v_pk_add_f32 v[4:5], v[16:17], v[14:15]
	v_pk_mul_f32 v[14:15], v[10:11], v[10:11]
	v_pk_mul_f32 v[16:17], v[12:13], v[12:13]
	v_mov_b32_e32 v18, v14
	v_mov_b32_e32 v19, v16
	v_mov_b32_e32 v16, v15
	v_pk_add_f32 v[14:15], v[18:19], v[16:17]
	v_add_f32_e32 v4, v4, v5
	v_add_f32_e32 v4, v4, v15
	v_add_f32_e32 v4, v14, v4
	v_pk_add_f32 v[70:71], v[74:75], v[70:71]
	v_pk_add_f32 v[72:73], v[76:77], v[72:73]
	v_add_f32_dpp v4, v4, v4 quad_perm:[1,0,3,2] row_mask:0xf bank_mask:0xf bound_ctrl:1
	v_xor_b32_e32 v75, 0x80000000, v69
	v_xor_b32_e32 v74, 0x80000000, v68
	v_add_f32_dpp v4, v4, v4 quad_perm:[2,3,0,1] row_mask:0xf bank_mask:0xf bound_ctrl:1
	v_pk_add_f32 v[86:87], v[90:91], v[86:87]
	v_pk_add_f32 v[88:89], v[92:93], v[88:89]
	v_add_f32_dpp v4, v4, v4 row_half_mirror row_mask:0xf bank_mask:0xf bound_ctrl:1
	v_add_f32_e32 v4, 0x358637bd, v4
	v_mul_f32_e32 v5, 0x4b800000, v4
	v_cmp_gt_f32_e32 vcc, s23, v4
	v_xor_b32_e32 v91, 0x80000000, v85
	v_xor_b32_e32 v90, 0x80000000, v84
	v_cndmask_b32_e32 v4, v4, v5, vcc
	v_rsq_f32_e32 v14, v4
	v_pk_fma_f32 v[72:73], v[72:73], 0.5, v[74:75] op_sel_hi:[1,0,1]
	v_pk_fma_f32 v[70:71], v[70:71], 0.5, v[66:67] op_sel_hi:[1,0,1] neg_lo:[0,0,1] neg_hi:[0,0,1]
	v_add_co_u32_e64 v4, s[8:9], s48, v6
	v_pk_fma_f32 v[88:89], v[88:89], 0.5, v[90:91] op_sel_hi:[1,0,1]
	v_pk_fma_f32 v[86:87], v[86:87], 0.5, v[82:83] op_sel_hi:[1,0,1] neg_lo:[0,0,1] neg_hi:[0,0,1]
	v_pk_fma_f32 v[68:69], v[80:81], v[72:73], v[68:69]
	v_pk_fma_f32 v[66:67], v[78:79], v[70:71], v[66:67]
	v_addc_co_u32_e64 v5, s[8:9], 0, v7, s[8:9]
	v_pk_fma_f32 v[84:85], v[96:97], v[88:89], v[84:85]
	v_pk_fma_f32 v[82:83], v[94:95], v[86:87], v[82:83]
	global_store_dwordx4 v[4:5], v[66:69], off nt
	global_store_dwordx4 v[4:5], v[82:85], off offset:16 nt
	v_mul_f32_e32 v4, 0x45800000, v14
	v_cndmask_b32_e32 v14, v14, v4, vcc
	v_add_co_u32_e32 v6, vcc, 0xd528000, v6
	v_pk_add_f32 v[110:111], v[114:115], v[110:111]
	v_pk_add_f32 v[112:113], v[116:117], v[112:113]
	v_xor_b32_e32 v115, 0x80000000, v105
	v_xor_b32_e32 v114, 0x80000000, v104
	v_pk_mul_f32 v[4:5], v[2:3], v[14:15] op_sel_hi:[1,0]
	v_pk_mul_f32 v[2:3], v[8:9], v[14:15] op_sel_hi:[1,0]
	v_addc_co_u32_e32 v7, vcc, 0, v7, vcc
	v_pk_fma_f32 v[112:113], v[112:113], 0.5, v[114:115] op_sel_hi:[1,0,1]
	v_pk_fma_f32 v[110:111], v[110:111], 0.5, v[102:103] op_sel_hi:[1,0,1] neg_lo:[0,0,1] neg_hi:[0,0,1]
	global_store_dwordx4 v[6:7], v[2:5], off nt
	v_pk_fma_f32 v[104:105], v[120:121], v[112:113], v[104:105]
	v_pk_fma_f32 v[102:103], v[118:119], v[110:111], v[102:103]
	v_pk_mul_f32 v[4:5], v[10:11], v[14:15] op_sel_hi:[1,0]
	v_pk_mul_f32 v[2:3], v[12:13], v[14:15] op_sel_hi:[1,0]
	global_store_dwordx4 v[6:7], v[2:5], off offset:16 nt
	s_nop 1
	v_lshl_add_u64 v[2:3], s[14:15], 0, v[156:157]
	s_and_saveexec_b64 s[8:9], s[4:5]
	s_xor_b64 s[8:9], exec, s[8:9]
	s_cbranch_execnz .LBB0_2699
	s_andn2_saveexec_b64 s[8:9], s[8:9]
	s_cbranch_execnz .LBB0_2700

.LBB0_2699:
	v_add_co_u32_e32 v6, vcc, 0xe2a7000, v2
	v_cvt_pk_bf16_f32 v4, v102, v103
	v_cvt_pk_bf16_f32 v5, v104, v105
	v_addc_co_u32_e32 v7, vcc, 0, v3, vcc
	global_store_dwordx2 v[6:7], v[4:5], off offset:3840 nt
	s_andn2_saveexec_b64 s[8:9], s[8:9]
	s_cbranch_execz .LBB0_2698
.LBB0_2700:
	v_add_f32_e32 v4, v102, v102
	v_add_f32_e32 v5, v103, v103
	v_add_f32_e32 v6, v104, v104
	v_add_f32_e32 v7, v105, v105
	v_mul_f32_e32 v4, 0x3fb8aa3b, v4
	v_mul_f32_e32 v5, 0x3fb8aa3b, v5
	v_mul_f32_e32 v6, 0x3fb8aa3b, v6
	v_mul_f32_e32 v7, 0x3fb8aa3b, v7
	v_exp_f32_e32 v4, v4
	v_exp_f32_e32 v5, v5
	v_exp_f32_e32 v6, v6
	v_exp_f32_e32 v7, v7
	v_add_f32_e32 v4, 1.0, v4
	v_add_f32_e32 v5, 1.0, v5
	v_add_f32_e32 v6, 1.0, v6
	v_add_f32_e32 v7, 1.0, v7
	v_rcp_f32_e32 v4, v4
	v_rcp_f32_e32 v5, v5
	v_rcp_f32_e32 v6, v6
	v_rcp_f32_e32 v7, v7
	v_pk_fma_f32 v[4:5], v[4:5], 2.0, 1.0 op_sel_hi:[1,0,0] neg_lo:[1,0,0] neg_hi:[1,0,0]
	s_nop 0
	v_cvt_pk_bf16_f32 v4, v4, v5
	v_pk_fma_f32 v[6:7], v[6:7], 2.0, 1.0 op_sel_hi:[1,0,0] neg_lo:[1,0,0] neg_hi:[1,0,0]
	s_nop 0
	v_cvt_pk_bf16_f32 v5, v6, v7
	v_add_co_u32_e32 v6, vcc, 0xe128000, v2
	s_nop 1
	v_addc_co_u32_e32 v7, vcc, 0, v3, vcc
	global_store_dwordx2 v[6:7], v[4:5], off nt
	s_or_b64 exec, exec, s[8:9]
	s_and_saveexec_b64 s[8:9], s[2:3]
	s_cbranch_execz .LBB0_2637
.LBB0_2701:
	v_mul_f32_e32 v4, 0xbfb8aa3b, v124
	v_mul_f32_e32 v5, 0xbfb8aa3b, v125
	v_mul_f32_e32 v6, 0xbfb8aa3b, v122
	v_mul_f32_e32 v7, 0xbfb8aa3b, v123
	v_exp_f32_e32 v4, v4
	v_exp_f32_e32 v5, v5
	v_exp_f32_e32 v6, v6
	v_exp_f32_e32 v7, v7
	v_add_f32_e32 v4, 1.0, v4
	v_add_f32_e32 v5, 1.0, v5
	v_add_f32_e32 v6, 1.0, v6
	v_add_f32_e32 v7, 1.0, v7
	v_rcp_f32_e32 v4, v4
	v_rcp_f32_e32 v5, v5
	v_rcp_f32_e32 v6, v6
	v_rcp_f32_e32 v7, v7
	v_add_co_u32_e32 v2, vcc, 0xe428000, v2
	v_cvt_pk_bf16_f32 v4, v4, v5
	v_cvt_pk_bf16_f32 v5, v6, v7
	v_addc_co_u32_e32 v3, vcc, 0, v3, vcc
	global_store_dwordx2 v[2:3], v[4:5], off nt
	s_branch .LBB0_2637
